# spatial LN-stats preamble: all 24 partial-stat loads issued before the ordered summation (one latency round instead of ~4), same add order
# baseline (speedup 1.0000x reference)
; #define LAS __attribute__((address_space(3)))
;     ...
;     for (int e = tid; e < nitems * 128; e += 512) { const int it = e >> 7, tk = e & 127; const size_t tok = (size_t)(n0 + it * nstep) * 128 + tk;
;         float s_ = 0.f, q_ = 0.f;
; #pragma unroll
;         for (int pi = 0; pi < 24; ++pi) { const f32x2v v_ = part[(size_t)pi * T + tok]; s_ += v_.x; q_ += v_.y; }
;         const float m_ = s_ * (1.0f / 3072.0f), var_ = q_ * (1.0f / 3072.0f) - m_ * m_;
;         LAS float* mu_ = (LAS float*)(lds + MU + it * 1024); mu_[tk] = m_; mu_[128 + tk] = rsqrtf(var_ + EPS); }
.LBB0_361:
	v_ashrrev_i32_e32 v27, 7, v26
	v_mul_lo_u32 v4, v27, s2
	v_add_u32_e32 v4, s10, v4
	v_ashrrev_i32_e32 v5, 31, v4
	v_lshlrev_b64 v[4:5], 10, v[4:5]
	v_lshl_add_u64 v[4:5], v[2:3], 0, v[4:5]
	global_load_dwordx2 v[6:7], v[4:5], off
	v_add_co_u32_e32 v32, vcc, 0x40000, v4
	s_nop 1
	v_addc_co_u32_e32 v33, vcc, 0, v5, vcc
	global_load_dwordx2 v[32:33], v[32:33], off
	v_add_co_u32_e32 v34, vcc, 0x80000, v4
	s_nop 1
	v_addc_co_u32_e32 v35, vcc, 0, v5, vcc
	global_load_dwordx2 v[34:35], v[34:35], off
	v_add_co_u32_e32 v36, vcc, 0xc0000, v4
	s_nop 1
	v_addc_co_u32_e32 v37, vcc, 0, v5, vcc
	global_load_dwordx2 v[36:37], v[36:37], off
	v_add_co_u32_e32 v38, vcc, 0x100000, v4
	s_nop 1
	v_addc_co_u32_e32 v39, vcc, 0, v5, vcc
	global_load_dwordx2 v[38:39], v[38:39], off
	v_add_co_u32_e32 v40, vcc, 0x140000, v4
	s_nop 1
	v_addc_co_u32_e32 v41, vcc, 0, v5, vcc
	global_load_dwordx2 v[40:41], v[40:41], off
	v_add_co_u32_e32 v42, vcc, 0x180000, v4
	s_nop 1
	v_addc_co_u32_e32 v43, vcc, 0, v5, vcc
	global_load_dwordx2 v[42:43], v[42:43], off
	v_add_co_u32_e32 v44, vcc, 0x1c0000, v4
	s_nop 1
	v_addc_co_u32_e32 v45, vcc, 0, v5, vcc
	global_load_dwordx2 v[44:45], v[44:45], off
	v_add_co_u32_e32 v46, vcc, 0x200000, v4
	s_nop 1
	v_addc_co_u32_e32 v47, vcc, 0, v5, vcc
	global_load_dwordx2 v[46:47], v[46:47], off
	v_add_co_u32_e32 v48, vcc, 0x240000, v4
	s_nop 1
	v_addc_co_u32_e32 v49, vcc, 0, v5, vcc
	global_load_dwordx2 v[48:49], v[48:49], off
	v_add_co_u32_e32 v50, vcc, 0x280000, v4
	s_nop 1
	v_addc_co_u32_e32 v51, vcc, 0, v5, vcc
	global_load_dwordx2 v[50:51], v[50:51], off
	v_add_co_u32_e32 v54, vcc, 0x2c0000, v4
	s_nop 1
	v_addc_co_u32_e32 v55, vcc, 0, v5, vcc
	global_load_dwordx2 v[54:55], v[54:55], off
	v_add_co_u32_e32 v56, vcc, 0x300000, v4
	s_nop 1
	v_addc_co_u32_e32 v57, vcc, 0, v5, vcc
	global_load_dwordx2 v[56:57], v[56:57], off
	v_add_co_u32_e32 v58, vcc, 0x340000, v4
	s_nop 1
	v_addc_co_u32_e32 v59, vcc, 0, v5, vcc
	global_load_dwordx2 v[58:59], v[58:59], off
	v_add_co_u32_e32 v60, vcc, 0x380000, v4
	s_nop 1
	v_addc_co_u32_e32 v61, vcc, 0, v5, vcc
	global_load_dwordx2 v[60:61], v[60:61], off
	v_add_co_u32_e32 v62, vcc, 0x3c0000, v4
	s_nop 1
	v_addc_co_u32_e32 v63, vcc, 0, v5, vcc
	global_load_dwordx2 v[62:63], v[62:63], off
	v_add_co_u32_e32 v68, vcc, 0x400000, v4
	s_nop 1
	v_addc_co_u32_e32 v69, vcc, 0, v5, vcc
	global_load_dwordx2 v[68:69], v[68:69], off
	v_add_co_u32_e32 v70, vcc, 0x440000, v4
	s_nop 1
	v_addc_co_u32_e32 v71, vcc, 0, v5, vcc
	global_load_dwordx2 v[70:71], v[70:71], off
	v_add_co_u32_e32 v72, vcc, 0x480000, v4
	s_nop 1
	v_addc_co_u32_e32 v73, vcc, 0, v5, vcc
	global_load_dwordx2 v[72:73], v[72:73], off
	v_add_co_u32_e32 v74, vcc, 0x4c0000, v4
	s_nop 1
	v_addc_co_u32_e32 v75, vcc, 0, v5, vcc
	global_load_dwordx2 v[74:75], v[74:75], off
	v_add_co_u32_e32 v76, vcc, 0x500000, v4
	s_nop 1
	v_addc_co_u32_e32 v77, vcc, 0, v5, vcc
	global_load_dwordx2 v[76:77], v[76:77], off
	v_add_co_u32_e32 v78, vcc, 0x540000, v4
	s_nop 1
	v_addc_co_u32_e32 v79, vcc, 0, v5, vcc
	global_load_dwordx2 v[78:79], v[78:79], off
	v_add_co_u32_e32 v80, vcc, 0x580000, v4
	s_nop 1
	v_addc_co_u32_e32 v81, vcc, 0, v5, vcc
	global_load_dwordx2 v[80:81], v[80:81], off
	v_add_co_u32_e32 v82, vcc, 0x5c0000, v4
	s_nop 1
	v_addc_co_u32_e32 v83, vcc, 0, v5, vcc
	global_load_dwordx2 v[82:83], v[82:83], off
	v_add_u32_e32 v26, 0x200, v26
	s_mov_b32 s22, 0x39aaaaab
	s_waitcnt vmcnt(23)
	v_pk_add_f32 v[6:7], v[6:7], 0 op_sel_hi:[1,0]
	s_waitcnt vmcnt(22)
	v_pk_add_f32 v[6:7], v[6:7], v[32:33]
	s_waitcnt vmcnt(21)
	v_pk_add_f32 v[6:7], v[6:7], v[34:35]
	s_waitcnt vmcnt(20)
	v_pk_add_f32 v[6:7], v[6:7], v[36:37]
	s_waitcnt vmcnt(19)
	v_pk_add_f32 v[6:7], v[6:7], v[38:39]
	s_waitcnt vmcnt(18)
	v_pk_add_f32 v[6:7], v[6:7], v[40:41]
	s_waitcnt vmcnt(17)
	v_pk_add_f32 v[6:7], v[6:7], v[42:43]
	s_waitcnt vmcnt(16)
	v_pk_add_f32 v[6:7], v[6:7], v[44:45]
	s_waitcnt vmcnt(15)
	v_pk_add_f32 v[6:7], v[6:7], v[46:47]
	s_waitcnt vmcnt(14)
	v_pk_add_f32 v[6:7], v[6:7], v[48:49]
	s_waitcnt vmcnt(13)
	v_pk_add_f32 v[6:7], v[6:7], v[50:51]
	s_waitcnt vmcnt(12)
	v_pk_add_f32 v[6:7], v[6:7], v[54:55]
	s_waitcnt vmcnt(11)
	v_pk_add_f32 v[6:7], v[6:7], v[56:57]
	s_waitcnt vmcnt(10)
	v_pk_add_f32 v[6:7], v[6:7], v[58:59]
	s_waitcnt vmcnt(9)
	v_pk_add_f32 v[6:7], v[6:7], v[60:61]
	s_waitcnt vmcnt(8)
	v_pk_add_f32 v[6:7], v[6:7], v[62:63]
	s_waitcnt vmcnt(7)
	v_pk_add_f32 v[6:7], v[6:7], v[68:69]
	s_waitcnt vmcnt(6)
	v_pk_add_f32 v[6:7], v[6:7], v[70:71]
	s_waitcnt vmcnt(5)
	v_pk_add_f32 v[6:7], v[6:7], v[72:73]
	s_waitcnt vmcnt(4)
	v_pk_add_f32 v[6:7], v[6:7], v[74:75]
	s_waitcnt vmcnt(3)
	v_pk_add_f32 v[6:7], v[6:7], v[76:77]
	s_waitcnt vmcnt(2)
	v_pk_add_f32 v[6:7], v[6:7], v[78:79]
	s_waitcnt vmcnt(1)
	v_pk_add_f32 v[6:7], v[6:7], v[80:81]
	s_waitcnt vmcnt(0)
	v_pk_add_f32 v[4:5], v[6:7], v[82:83]
	s_nop 0
	v_pk_mul_f32 v[4:5], v[4:5], s[22:23] op_sel_hi:[1,0]
	v_lshl_add_u32 v6, v27, 10, v0
	v_fma_f32 v5, -v4, v4, v5
	v_add_f32_e32 v5, 0x358637bd, v5
	v_cmp_gt_f32_e32 vcc, s15, v5
	v_mul_f32_e32 v7, 0x4b800000, v5
	s_nop 0
	v_cndmask_b32_e32 v5, v5, v7, vcc
	v_rsq_f32_e32 v5, v5
	s_nop 0
	v_mul_f32_e32 v7, 0x45800000, v5
	v_cndmask_b32_e32 v5, v5, v7, vcc
	v_cmp_le_i32_e32 vcc, s21, v26
	s_or_b64 s[18:19], vcc, s[18:19]
	ds_write2st64_b32 v6, v4, v5 offset1:2
	s_andn2_b64 exec, exec, s[18:19]
	s_cbranch_execnz .LBB0_361
